# post phase rwkv part: both heads of a trip fetched in one batch (neighbour rows unconditional + masked) and evaluated side by side
# speedup vs baseline: 1.4684x; 1.0121x over previous
; __device__ __forceinline__ f32x4 unpk4(u32x2 v) { return (f32x4){bflo(v.x), bfhi(v.x), bflo(v.y), bfhi(v.y)}; }
; __device__ __forceinline__ u32x2 pk4(f32x4 v) { u32x2 r; r.x = pk2(v[0], v[1]); r.y = pk2(v[2], v[3]); return r; }
; __device__ __forceinline__ void phase_post(const PP& p, int l) {
;     ...
;         for (int tg = 0; tg < 4; ++tg) {
;             const int row = item * 16 + tg * 4 + tk, b = row / TT, j = row - b * TT;
;             const bool hp = (j != 0) && (j != CTX), hn = (j != CTX - 1) && (j != TT - 1);
;             const bf16_t* gr = grw_row(p.ws, row);
; #pragma unroll 2
;             for (int h = 0; h < 6; ++h) {
;                 const int c = h * 64 + 4 * c4;
;                 f32x4 y = unpk4(*(const u32x2*)(YO + (size_t)row * 384 + c)) + unpk4(*(const u32x2*)(YO + YS + (size_t)row * 384 + c));
;                 const float mean = red16(y[0] + y[1] + y[2] + y[3]) * (1.f / 64.f);
;                 y = y - mean;
;                 const float rstd = __builtin_amdgcn_rsqf(red16(y[0] * y[0] + y[1] * y[1] + y[2] * y[2] + y[3] * y[3]) * (1.f / 64.f) + 64e-5f);
;                 const float bon = BC[(size_t)row * 6 + h] + BC[(size_t)MROWS * 6 + (size_t)row * 6 + h];
;                 const f32x4 lg = *(const f32x4*)(p.in[I_LNG] + l * 384 + c), lb = *(const f32x4*)(p.in[I_LNB] + l * 384 + c);
;                 const f32x4 vs = shiftmix(ld3(Z, row, hp, hn, 768 + c), mu + 768 + c);
;                 const f32x4 ga = unpk4(*(const u32x2*)(gr + c));
;                 *(u32x2*)(MIX + (size_t)row * DM + c) = pk4((y * rstd * lg + lb + vs * bon) * ga);
;             }
.LBB0_1020:
	v_lshl_add_u64 v[228:229], s[14:15], 0, v[40:41]
	s_mov_b32 s7, 0x1517c000
	v_add_co_u32_e32 v230, vcc, s7, v228
	s_nop 1
	v_addc_co_u32_e32 v231, vcc, 0, v229, vcc
	s_mov_b32 s7, 0x138bc000
	v_add_co_u32_e32 v228, vcc, s7, v228
	s_nop 1
	v_addc_co_u32_e32 v229, vcc, 0, v229, vcc
	v_lshl_add_u64 v[232:233], s[14:15], 0, v[42:43]
	s_mov_b32 s7, 0x36aa000
	v_add_co_u32_e32 v234, vcc, s7, v232
	s_nop 1
	v_addc_co_u32_e32 v235, vcc, 0, v233, vcc
	s_mov_b32 s7, 0x35e4000
	v_add_co_u32_e32 v232, vcc, s7, v232
	s_nop 1
	v_addc_co_u32_e32 v233, vcc, 0, v233, vcc
	v_lshl_add_u64 v[236:237], s[14:15], 0, v[38:39]
	s_mov_b32 s7, 0x7970000
	v_add_co_u32_e32 v238, vcc, s7, v236
	s_nop 1
	v_addc_co_u32_e32 v239, vcc, 0, v237, vcc
	s_mov_b32 s7, 0x796e000
	v_add_co_u32_e32 v240, vcc, s7, v236
	s_nop 1
	v_addc_co_u32_e32 v241, vcc, 0, v237, vcc
	s_mov_b32 s7, 0x7971000
	v_add_co_u32_e32 v242, vcc, s7, v236
	s_nop 1
	v_addc_co_u32_e32 v243, vcc, 0, v237, vcc
	s_waitcnt lgkmcnt(0)
	v_readfirstlane_b32 s28, v2
	v_readfirstlane_b32 s29, v3
	s_nop 1
	v_lshl_add_u64 v[244:245], s[28:29], 0, v[22:23]
	v_readfirstlane_b32 s28, v4
	v_readfirstlane_b32 s29, v5
	v_lshl_add_u64 v[244:245], v[244:245], 0, s[26:27]
	v_lshl_add_u64 v[248:249], v[20:21], 0, s[26:27]
	v_lshl_add_u64 v[246:247], s[28:29], 0, v[22:23]
	v_lshl_add_u64 v[246:247], v[246:247], 0, s[26:27]
	v_lshl_add_u64 v[250:251], s[14:15], 0, v[44:45]
	global_load_dwordx2 v[84:85], v[228:229], off
	global_load_dwordx2 v[86:87], v[230:231], off
	global_load_dwordx2 v[88:89], v[238:239], off offset:1536
	global_load_dwordx2 v[90:91], v[240:241], off offset:3792
	global_load_dwordx2 v[92:93], v[242:243], off offset:3376
	global_load_dwordx2 v[94:95], v[250:251], off
	global_load_dword v96, v[232:233], off
	global_load_dword v97, v[234:235], off
	global_load_dwordx4 v[98:101], v[244:245], off
	global_load_dwordx4 v[102:105], v[246:247], off
	global_load_dwordx4 v[106:109], v[248:249], off offset:3072
	global_load_dwordx2 v[182:183], v[228:229], off offset:128
	global_load_dwordx2 v[184:185], v[230:231], off offset:128
	global_load_dwordx2 v[186:187], v[238:239], off offset:1664
	global_load_dwordx2 v[188:189], v[240:241], off offset:3920
	global_load_dwordx2 v[190:191], v[242:243], off offset:3504
	global_load_dwordx2 v[192:193], v[250:251], off offset:128
	global_load_dword v194, v[232:233], off offset:4
	global_load_dword v195, v[234:235], off offset:4
	global_load_dwordx4 v[196:199], v[244:245], off offset:256
	global_load_dwordx4 v[200:203], v[246:247], off offset:256
	global_load_dwordx4 v[204:207], v[248:249], off offset:3328
	v_lshl_add_u64 v[228:229], s[14:15], 0, v[36:37]
	v_add_co_u32_e32 v228, vcc, s17, v228
	s_nop 1
	v_addc_co_u32_e32 v229, vcc, 0, v229, vcc
	s_waitcnt vmcnt(0)
	v_cndmask_b32_e64 v90, 0, v90, s[34:35]
	v_cndmask_b32_e64 v188, 0, v188, s[34:35]
	v_cndmask_b32_e64 v91, 0, v91, s[34:35]
	v_cndmask_b32_e64 v189, 0, v189, s[34:35]
	v_cndmask_b32_e64 v92, 0, v92, s[36:37]
	v_cndmask_b32_e64 v190, 0, v190, s[36:37]
	v_cndmask_b32_e64 v93, 0, v93, s[36:37]
	v_cndmask_b32_e64 v191, 0, v191, s[36:37]
	v_lshlrev_b32_e32 v110, 16, v84
	v_lshlrev_b32_e32 v208, 16, v182
	v_and_b32_e32 v111, 0xffff0000, v84
	v_and_b32_e32 v209, 0xffff0000, v182
	v_lshlrev_b32_e32 v112, 16, v85
	v_lshlrev_b32_e32 v210, 16, v183
	v_and_b32_e32 v113, 0xffff0000, v85
	v_and_b32_e32 v211, 0xffff0000, v183
	v_lshlrev_b32_e32 v114, 16, v86
	v_lshlrev_b32_e32 v212, 16, v184
	v_and_b32_e32 v115, 0xffff0000, v86
	v_and_b32_e32 v213, 0xffff0000, v184
	v_lshlrev_b32_e32 v116, 16, v87
	v_lshlrev_b32_e32 v214, 16, v185
	v_and_b32_e32 v117, 0xffff0000, v87
	v_and_b32_e32 v215, 0xffff0000, v185
	v_pk_add_f32 v[110:111], v[110:111], v[114:115]
	v_pk_add_f32 v[208:209], v[208:209], v[212:213]
	v_pk_add_f32 v[112:113], v[112:113], v[116:117]
	v_pk_add_f32 v[210:211], v[210:211], v[214:215]
	v_add_f32_e32 v126, v110, v111
	v_add_f32_e32 v224, v208, v209
	v_add_f32_e32 v126, v112, v126
	v_add_f32_e32 v224, v210, v224
	v_add_f32_e32 v126, v113, v126
	v_add_f32_e32 v224, v211, v224
	v_lshlrev_b32_e32 v118, 16, v88
	v_lshlrev_b32_e32 v216, 16, v186
	v_and_b32_e32 v119, 0xffff0000, v88
	v_and_b32_e32 v217, 0xffff0000, v186
	v_lshlrev_b32_e32 v120, 16, v89
	v_lshlrev_b32_e32 v218, 16, v187
	v_and_b32_e32 v121, 0xffff0000, v89
	v_and_b32_e32 v219, 0xffff0000, v187
	s_nop 0
	v_add_f32_dpp v126, v126, v126 quad_perm:[1,0,3,2] row_mask:0xf bank_mask:0xf bound_ctrl:1
	v_add_f32_dpp v224, v224, v224 quad_perm:[1,0,3,2] row_mask:0xf bank_mask:0xf bound_ctrl:1
	s_nop 0
	v_add_f32_dpp v126, v126, v126 quad_perm:[2,3,0,1] row_mask:0xf bank_mask:0xf bound_ctrl:1
	v_add_f32_dpp v224, v224, v224 quad_perm:[2,3,0,1] row_mask:0xf bank_mask:0xf bound_ctrl:1
	s_nop 0
	v_add_f32_dpp v126, v126, v126 row_half_mirror row_mask:0xf bank_mask:0xf bound_ctrl:1
	v_add_f32_dpp v224, v224, v224 row_half_mirror row_mask:0xf bank_mask:0xf bound_ctrl:1
	s_nop 0
	v_add_f32_dpp v126, v126, v126 row_ror:8 row_mask:0xf bank_mask:0xf bound_ctrl:1
	v_add_f32_dpp v224, v224, v224 row_ror:8 row_mask:0xf bank_mask:0xf bound_ctrl:1
; __device__ __forceinline__ f32x4 unpk4(u32x2 v) { return (f32x4){bflo(v.x), bfhi(v.x), bflo(v.y), bfhi(v.y)}; }
; __device__ __forceinline__ u32x2 pk4(f32x4 v) { u32x2 r; r.x = pk2(v[0], v[1]); r.y = pk2(v[2], v[3]); return r; }
; __device__ __forceinline__ void phase_post(const PP& p, int l) {
;     ...
;             for (int h = 0; h < 6; ++h) {
;                 const int c = h * 64 + 4 * c4;
;                 f32x4 y = unpk4(*(const u32x2*)(YO + (size_t)row * 384 + c)) + unpk4(*(const u32x2*)(YO + YS + (size_t)row * 384 + c));
;                 const float mean = red16(y[0] + y[1] + y[2] + y[3]) * (1.f / 64.f);
;                 y = y - mean;
;                 const float rstd = __builtin_amdgcn_rsqf(red16(y[0] * y[0] + y[1] * y[1] + y[2] * y[2] + y[3] * y[3]) * (1.f / 64.f) + 64e-5f);
;                 const float bon = BC[(size_t)row * 6 + h] + BC[(size_t)MROWS * 6 + (size_t)row * 6 + h];
;                 const f32x4 lg = *(const f32x4*)(p.in[I_LNG] + l * 384 + c), lb = *(const f32x4*)(p.in[I_LNB] + l * 384 + c);
;                 const f32x4 vs = shiftmix(ld3(Z, row, hp, hn, 768 + c), mu + 768 + c);
;                 const f32x4 ga = unpk4(*(const u32x2*)(gr + c));
;                 *(u32x2*)(MIX + (size_t)row * DM + c) = pk4((y * rstd * lg + lb + vs * bon) * ga);
;             }
	v_fmamk_f32 v111, v126, 0xbc800000, v111
	v_fmamk_f32 v209, v224, 0xbc800000, v209
	v_fmamk_f32 v113, v126, 0xbc800000, v113
	v_fmamk_f32 v211, v224, 0xbc800000, v211
	v_fmac_f32_e32 v112, 0xbc800000, v126
	v_fmac_f32_e32 v210, 0xbc800000, v224
	v_fmac_f32_e32 v110, 0xbc800000, v126
	v_fmac_f32_e32 v208, 0xbc800000, v224
	v_mul_f32_e32 v127, v111, v111
	v_mul_f32_e32 v225, v209, v209
	v_fmac_f32_e32 v127, v110, v110
	v_fmac_f32_e32 v225, v208, v208
	v_fmac_f32_e32 v127, v112, v112
	v_fmac_f32_e32 v225, v210, v210
	v_fmac_f32_e32 v127, v113, v113
	v_fmac_f32_e32 v225, v211, v211
	v_lshlrev_b32_e32 v122, 16, v90
	v_lshlrev_b32_e32 v220, 16, v188
	v_and_b32_e32 v123, 0xffff0000, v90
	v_and_b32_e32 v221, 0xffff0000, v188
	v_lshlrev_b32_e32 v124, 16, v91
	v_lshlrev_b32_e32 v222, 16, v189
	v_and_b32_e32 v125, 0xffff0000, v91
	v_and_b32_e32 v223, 0xffff0000, v189
	s_nop 0
	v_add_f32_dpp v127, v127, v127 quad_perm:[1,0,3,2] row_mask:0xf bank_mask:0xf bound_ctrl:1
	v_add_f32_dpp v225, v225, v225 quad_perm:[1,0,3,2] row_mask:0xf bank_mask:0xf bound_ctrl:1
	s_nop 0
	v_add_f32_dpp v127, v127, v127 quad_perm:[2,3,0,1] row_mask:0xf bank_mask:0xf bound_ctrl:1
	v_add_f32_dpp v225, v225, v225 quad_perm:[2,3,0,1] row_mask:0xf bank_mask:0xf bound_ctrl:1
	s_nop 0
	v_add_f32_dpp v127, v127, v127 row_half_mirror row_mask:0xf bank_mask:0xf bound_ctrl:1
	v_add_f32_dpp v225, v225, v225 row_half_mirror row_mask:0xf bank_mask:0xf bound_ctrl:1
	s_nop 0
	v_add_f32_dpp v127, v127, v127 row_ror:8 row_mask:0xf bank_mask:0xf bound_ctrl:1
	v_add_f32_dpp v225, v225, v225 row_ror:8 row_mask:0xf bank_mask:0xf bound_ctrl:1
	v_fmamk_f32 v127, v127, 0x3c800000, v173
	v_fmamk_f32 v225, v225, 0x3c800000, v173
	v_rsq_f32_e32 v128, v127
	v_rsq_f32_e32 v226, v225
	v_lshlrev_b32_e32 v114, 16, v92
	v_lshlrev_b32_e32 v212, 16, v190
	v_and_b32_e32 v115, 0xffff0000, v92
	v_and_b32_e32 v213, 0xffff0000, v190
	v_lshlrev_b32_e32 v116, 16, v93
	v_lshlrev_b32_e32 v214, 16, v191
	v_and_b32_e32 v117, 0xffff0000, v93
	v_and_b32_e32 v215, 0xffff0000, v191
	v_pk_add_f32 v[122:123], v[122:123], v[114:115]
	v_pk_add_f32 v[220:221], v[220:221], v[212:213]
	v_pk_add_f32 v[124:125], v[124:125], v[116:117]
	v_pk_add_f32 v[222:223], v[222:223], v[214:215]
	v_xor_b32_e32 v114, 0x80000000, v118
	v_xor_b32_e32 v212, 0x80000000, v216
	v_xor_b32_e32 v115, 0x80000000, v119
	v_xor_b32_e32 v213, 0x80000000, v217
	v_xor_b32_e32 v116, 0x80000000, v120
	v_xor_b32_e32 v214, 0x80000000, v218
	v_xor_b32_e32 v117, 0x80000000, v121
	v_xor_b32_e32 v215, 0x80000000, v219
	v_pk_fma_f32 v[122:123], v[122:123], 0.5, v[114:115] op_sel_hi:[1,0,1]
	v_pk_fma_f32 v[220:221], v[220:221], 0.5, v[212:213] op_sel_hi:[1,0,1]
	v_pk_fma_f32 v[124:125], v[124:125], 0.5, v[116:117] op_sel_hi:[1,0,1]
	v_pk_fma_f32 v[222:223], v[222:223], 0.5, v[214:215] op_sel_hi:[1,0,1]
	v_pk_fma_f32 v[122:123], v[106:107], v[122:123], v[118:119]
	v_pk_fma_f32 v[220:221], v[204:205], v[220:221], v[216:217]
	v_pk_fma_f32 v[124:125], v[108:109], v[124:125], v[120:121]
	v_pk_fma_f32 v[222:223], v[206:207], v[222:223], v[218:219]
	v_add_f32_e32 v126, v96, v97
	v_add_f32_e32 v224, v194, v195
	v_pk_mul_f32 v[110:111], v[110:111], v[128:129] op_sel_hi:[1,0]
	v_pk_mul_f32 v[208:209], v[208:209], v[226:227] op_sel_hi:[1,0]
	v_pk_mul_f32 v[112:113], v[112:113], v[128:129] op_sel_hi:[1,0]
	v_pk_mul_f32 v[210:211], v[210:211], v[226:227] op_sel_hi:[1,0]
	v_pk_fma_f32 v[110:111], v[98:99], v[110:111], v[102:103]
	v_pk_fma_f32 v[208:209], v[196:197], v[208:209], v[200:201]
	v_pk_fma_f32 v[112:113], v[100:101], v[112:113], v[104:105]
	v_pk_fma_f32 v[210:211], v[198:199], v[210:211], v[202:203]
	v_pk_fma_f32 v[110:111], v[126:127], v[122:123], v[110:111] op_sel_hi:[0,1,1]
	v_pk_fma_f32 v[208:209], v[224:225], v[220:221], v[208:209] op_sel_hi:[0,1,1]
	v_pk_fma_f32 v[112:113], v[126:127], v[124:125], v[112:113] op_sel_hi:[0,1,1]
	v_pk_fma_f32 v[210:211], v[224:225], v[222:223], v[210:211] op_sel_hi:[0,1,1]
	v_lshlrev_b32_e32 v114, 16, v94
	v_lshlrev_b32_e32 v212, 16, v192
	v_and_b32_e32 v115, 0xffff0000, v94
	v_and_b32_e32 v213, 0xffff0000, v192
	v_lshlrev_b32_e32 v116, 16, v95
	v_lshlrev_b32_e32 v214, 16, v193
	v_and_b32_e32 v117, 0xffff0000, v95
	v_and_b32_e32 v215, 0xffff0000, v193
	v_pk_mul_f32 v[110:111], v[110:111], v[114:115]
	v_pk_mul_f32 v[208:209], v[208:209], v[212:213]
	v_pk_mul_f32 v[112:113], v[112:113], v[116:117]
	v_pk_mul_f32 v[210:211], v[210:211], v[214:215]
	v_cvt_pk_bf16_f32 v110, v110, v111
	v_cvt_pk_bf16_f32 v208, v208, v209
	v_cvt_pk_bf16_f32 v111, v112, v113
	v_cvt_pk_bf16_f32 v209, v210, v211
	global_store_dwordx2 v[228:229], v[110:111], off
	global_store_dwordx2 v[228:229], v[208:209], off offset:128
	s_add_u32 s26, s26, 0x200
	s_addc_u32 s27, s27, 0
	v_lshl_add_u64 v[36:37], v[36:37], 0, s[8:9]
	v_lshl_add_u64 v[38:39], v[38:39], 0, s[8:9]
	v_lshl_add_u64 v[40:41], v[40:41], 0, s[8:9]
	v_lshl_add_u64 v[44:45], v[44:45], 0, s[8:9]
	v_lshl_add_u64 v[42:43], v[42:43], 0, 8
	s_cmpk_eq_i32 s26, 0x600
	s_cbranch_scc1 .LBB0_1017
	s_branch .LBB0_1020
